# LN2 slab loads batched 16-deep; attention: one wait for gate loads, no per-store vmcnt ladder; P0 stores write-through; HGRN chain prefetch with scalar row addressing issued a chunk early; pass-0 stat
# speedup vs baseline: 1.0117x; 1.0117x over previous
.LBB0_7:
	s_or_b64 exec, exec, s[10:11]
	ds_write2_b32 v81, v62, v63 offset1:1
	ds_write2_b32 v81, v64, v65 offset0:2 offset1:3
	v_add_u32_e32 v62, 0x420, v81
	ds_write2_b32 v62, v58, v59 offset1:1
	v_add_u32_e32 v58, 0x428, v81
	ds_write2_b32 v58, v60, v61 offset1:1
	v_add_u32_e32 v58, 0x840, v81
	ds_write2_b32 v58, v54, v55 offset1:1
	v_add_u32_e32 v54, 0x848, v81
	ds_write2_b32 v54, v56, v57 offset1:1
	v_add_u32_e32 v54, 0xc60, v81
	ds_write2_b32 v54, v50, v51 offset1:1
	v_add_u32_e32 v50, 0xc68, v81
	ds_write2_b32 v50, v52, v53 offset1:1
	v_add_u32_e32 v50, 0x1080, v81
	ds_write2_b32 v50, v38, v39 offset1:1
	v_add_u32_e32 v38, 0x1088, v81
	ds_write2_b32 v38, v40, v41 offset1:1
	v_add_u32_e32 v38, 0x14a0, v81
	ds_write2_b32 v38, v26, v27 offset1:1
	v_add_u32_e32 v26, 0x14a8, v81
	ds_write2_b32 v26, v28, v29 offset1:1
	v_add_u32_e32 v26, 0x18c0, v81
	ds_write2_b32 v26, v14, v15 offset1:1
	v_add_u32_e32 v14, 0x18c8, v81
	ds_write2_b32 v14, v16, v17 offset1:1
	v_add_u32_e32 v14, 0x1ce0, v81
	ds_write2_b32 v14, v10, v11 offset1:1
	v_add_u32_e32 v10, 0x1ce8, v81
	ds_write2_b32 v10, v12, v13 offset1:1
	s_waitcnt lgkmcnt(0)
	ds_read2_b32 v[10:11], v79 offset1:33
	v_ashrrev_i32_e32 v14, 31, v83
	s_waitcnt lgkmcnt(0)
	v_cvt_pk_bf16_f32 v10, v10, v11
	ds_read2_b32 v[12:13], v79 offset0:66 offset1:99
	v_add_u32_sdwa v14, v83, v14 dst_sel:DWORD dst_unused:UNUSED_PAD src0_sel:DWORD src1_sel:BYTE_3
	s_waitcnt lgkmcnt(0)
	v_cvt_pk_bf16_f32 v11, v12, v13
	ds_read2_b32 v[12:13], v79 offset0:132 offset1:165
	v_ashrrev_i32_e32 v15, 8, v14
	s_waitcnt lgkmcnt(0)
	v_cvt_pk_bf16_f32 v12, v12, v13
	v_mul_i32_i24_e32 v13, 0x100, v15
	v_sub_u32_e32 v13, v83, v13
	ds_read2_b32 v[16:17], v79 offset0:198 offset1:231
	v_lshlrev_b32_e32 v28, 5, v13
	s_waitcnt lgkmcnt(0)
	v_cvt_pk_bf16_f32 v13, v16, v17
	v_or_b32_e32 v16, v28, v75
	v_lshlrev_b32_e32 v14, 6, v15
	v_ashrrev_i32_e32 v17, 31, v16
	v_ashrrev_i32_e32 v15, 31, v14
	v_lshlrev_b64 v[16:17], 12, v[16:17]
	v_lshl_add_u64 v[16:17], s[70:71], 0, v[16:17]
	v_lshlrev_b64 v[14:15], 1, v[14:15]
	v_lshl_add_u64 v[16:17], v[16:17], 0, v[14:15]
	v_lshl_add_u64 v[16:17], v[16:17], 0, v[70:71]
	ds_read2_b32 v[26:27], v79 offset0:8 offset1:41
	global_store_dwordx4 v[16:17], v[10:13], off sc0 sc1
	s_and_b64 s[4:5], exec, vcc
	s_waitcnt vmcnt(4)
	v_mov_b64_e32 v[40:41], v[36:37]
	s_waitcnt lgkmcnt(0)
	v_cvt_pk_bf16_f32 v10, v26, v27
	ds_read2_b32 v[12:13], v79 offset0:74 offset1:107
	s_waitcnt lgkmcnt(0)
	v_cvt_pk_bf16_f32 v11, v12, v13
	ds_read2_b32 v[12:13], v79 offset0:140 offset1:173
	s_waitcnt lgkmcnt(0)
	v_cvt_pk_bf16_f32 v12, v12, v13
	ds_read2_b32 v[16:17], v79 offset0:206 offset1:239
	s_waitcnt lgkmcnt(0)
	v_cvt_pk_bf16_f32 v13, v16, v17
	v_or_b32_e32 v16, v28, v76
	v_ashrrev_i32_e32 v17, 31, v16
	v_lshlrev_b64 v[16:17], 12, v[16:17]
	v_lshl_add_u64 v[16:17], s[70:71], 0, v[16:17]
	v_lshl_add_u64 v[16:17], v[16:17], 0, v[14:15]
	v_lshl_add_u64 v[16:17], v[16:17], 0, v[70:71]
	ds_read2_b32 v[26:27], v79 offset0:16 offset1:49
	global_store_dwordx4 v[16:17], v[10:13], off sc0 sc1
	v_mov_b64_e32 v[52:53], v[20:21]
	v_mov_b64_e32 v[56:57], v[24:25]
	s_waitcnt lgkmcnt(0)
	v_cvt_pk_bf16_f32 v10, v26, v27
	ds_read2_b32 v[12:13], v79 offset0:82 offset1:115
	s_waitcnt lgkmcnt(0)
	v_cvt_pk_bf16_f32 v11, v12, v13
	ds_read2_b32 v[12:13], v79 offset0:148 offset1:181
	s_waitcnt lgkmcnt(0)
	v_cvt_pk_bf16_f32 v12, v12, v13
	ds_read2_b32 v[16:17], v79 offset0:214 offset1:247
	s_waitcnt lgkmcnt(0)
	v_cvt_pk_bf16_f32 v13, v16, v17
	v_or_b32_e32 v16, v28, v77
	v_ashrrev_i32_e32 v17, 31, v16
	v_lshlrev_b64 v[16:17], 12, v[16:17]
	v_lshl_add_u64 v[16:17], s[70:71], 0, v[16:17]
	v_lshl_add_u64 v[16:17], v[16:17], 0, v[14:15]
	v_lshl_add_u64 v[16:17], v[16:17], 0, v[70:71]
	ds_read2_b32 v[26:27], v79 offset0:24 offset1:57
	global_store_dwordx4 v[16:17], v[10:13], off sc0 sc1
	v_mov_b64_e32 v[60:61], v[4:5]
	v_mov_b64_e32 v[64:65], v[8:9]
	s_waitcnt lgkmcnt(0)
	v_cvt_pk_bf16_f32 v10, v26, v27
	ds_read2_b32 v[12:13], v79 offset0:90 offset1:123
	s_waitcnt lgkmcnt(0)
	v_cvt_pk_bf16_f32 v11, v12, v13
	ds_read2_b32 v[12:13], v79 offset0:156 offset1:189
	s_waitcnt lgkmcnt(0)
	v_cvt_pk_bf16_f32 v12, v12, v13
	ds_read2_b32 v[16:17], v79 offset0:222 offset1:255
	s_waitcnt lgkmcnt(0)
	v_cvt_pk_bf16_f32 v13, v16, v17
	v_or_b32_e32 v16, v28, v78
	v_ashrrev_i32_e32 v17, 31, v16
	v_lshlrev_b64 v[16:17], 12, v[16:17]
	v_lshl_add_u64 v[16:17], s[70:71], 0, v[16:17]
	v_lshl_add_u64 v[14:15], v[16:17], 0, v[14:15]
	v_lshl_add_u64 v[14:15], v[14:15], 0, v[70:71]
	global_store_dwordx4 v[14:15], v[10:13], off sc0 sc1
	s_waitcnt lgkmcnt(0)
	s_waitcnt vmcnt(5)
	v_mov_b64_e32 v[14:15], v[46:47]
	v_mov_b64_e32 v[26:27], v[30:31]
	s_waitcnt vmcnt(4)
	v_mov_b64_e32 v[10:11], v[42:43]
	s_or_b64 s[6:7], s[4:5], s[6:7]
	v_add_u32_e32 v80, s13, v80
	v_mov_b64_e32 v[12:13], v[44:45]
	v_mov_b64_e32 v[16:17], v[48:49]
	v_mov_b64_e32 v[28:29], v[32:33]
	v_mov_b64_e32 v[38:39], v[34:35]
	v_mov_b64_e32 v[50:51], v[18:19]
	v_mov_b64_e32 v[54:55], v[22:23]
	v_mov_b64_e32 v[58:59], v[2:3]
	v_mov_b64_e32 v[62:63], v[6:7]
	v_mov_b32_e32 v83, v73
	s_andn2_b64 exec, exec, s[6:7]
	s_cbranch_execz .LBB0_10

.LBB0_22:
	s_or_b64 exec, exec, s[6:7]
	s_add_i32 s16, s16, s68
	global_store_dwordx2 v[36:37], v[38:39], off sc0 sc1
	global_store_dwordx2 v[36:37], v[40:41], off offset:512 sc0 sc1
	global_store_dwordx2 v[36:37], v[42:43], off offset:1024 sc0 sc1
	global_store_dwordx2 v[36:37], v[44:45], off offset:1536 sc0 sc1
	global_store_dwordx2 v[36:37], v[46:47], off offset:2048 sc0 sc1
	global_store_dwordx2 v[36:37], v[48:49], off offset:2560 sc0 sc1
	global_store_dwordx2 v[36:37], v[50:51], off offset:3072 sc0 sc1
	global_store_dwordx2 v[36:37], v[52:53], off offset:3584 sc0 sc1
	v_add_u32_e32 v38, s16, v67
	v_cmp_lt_i32_e32 vcc, s15, v38
	s_or_b64 s[4:5], vcc, s[4:5]
	v_lshl_add_u64 v[36:37], v[36:37], 0, s[2:3]
	s_andn2_b64 exec, exec, s[4:5]
	s_cbranch_execz .LBB0_31

.LBB0_33:
	s_waitcnt vmcnt(14)
	v_lshl_add_u64 v[6:7], s[26:27], 0, v[4:5]
	v_add_co_u32_e32 v8, vcc, 0x2000, v6
	global_load_dword v1, v[6:7], off
	s_nop 0
	v_addc_co_u32_e32 v9, vcc, 0, v7, vcc
	v_add_co_u32_e32 v6, vcc, 0x4000, v6
	v_add_u32_e32 v2, s88, v2
	s_nop 0
	v_addc_co_u32_e32 v7, vcc, 0, v7, vcc
	global_load_dword v3, v[8:9], off
	s_nop 0
	global_load_dword v8, v[6:7], off
	v_cmp_lt_i32_e32 vcc, s10, v2
	s_or_b64 s[6:7], vcc, s[6:7]
	v_lshl_add_u64 v[6:7], s[2:3], 0, v[4:5]
	v_lshl_add_u64 v[4:5], v[4:5], 0, s[4:5]
	s_waitcnt vmcnt(0)
	v_max3_f32 v9, v1, v3, v8
	v_sub_f32_e32 v1, v1, v9
	v_sub_f32_e32 v3, v3, v9
	v_sub_f32_e32 v8, v8, v9
	v_mul_f32_e32 v1, 0x3fb8aa3b, v1
	v_mul_f32_e32 v3, 0x3fb8aa3b, v3
	v_mul_f32_e32 v8, 0x3fb8aa3b, v8
	v_exp_f32_e32 v1, v1
	v_exp_f32_e32 v3, v3
	v_exp_f32_e32 v8, v8
	v_add_f32_e32 v3, v1, v3
	v_add_f32_e32 v3, v8, v3
	v_div_scale_f32 v8, s[12:13], v3, v3, v1
	v_rcp_f32_e32 v9, v8
	v_div_scale_f32 v10, vcc, v1, v3, v1
	v_fma_f32 v11, -v8, v9, 1.0
	v_fmac_f32_e32 v9, v11, v9
	v_mul_f32_e32 v11, v10, v9
	v_fma_f32 v12, -v8, v11, v10
	v_fmac_f32_e32 v11, v12, v9
	v_fma_f32 v8, -v8, v11, v10
	v_div_fmas_f32 v8, v8, v9, v11
	v_div_fixup_f32 v1, v8, v3, v1
	global_store_dword v[6:7], v1, off sc0 sc1
	s_andn2_b64 exec, exec, s[6:7]
	s_cbranch_execnz .LBB0_33

.LBB0_372:
	s_add_i32 s93, s24, 1
	s_cmp_lt_u32 s93, s5
	s_cselect_b32 s93, s93, s24
	v_readfirstlane_b32 s92, v151
	s_lshl_b32 s93, s93, 6
	s_add_i32 s92, s92, s93
	s_lshl_b32 s93, s23, 12
	s_add_u32 s100, s6, s93
	s_addc_u32 s101, s7, 0
	s_add_u32 s10, s8, s93
	s_addc_u32 s11, s9, 0
	s_lshl_b32 s93, s93, 1
	s_add_u32 s98, s28, s93
	s_addc_u32 s99, s29, 0
	s_lshl_b32 s93, s92, 11
	v_or_b32_e32 v65, s93, v158
	v_lshlrev_b32_e32 v64, 2, v65
	v_lshlrev_b32_e32 v65, 1, v65
	v_add_u32_e32 v65, 0x1000, v65
	s_add_i32 s93, s92, 15
	s_cmp_lt_i32 s93, s18
	s_cbranch_scc0 .Lhgl_mslow_a
	s_mov_b64 s[64:65], -1
	s_mov_b64 s[66:67], -1
	s_mov_b64 s[68:69], -1
	s_mov_b64 s[70:71], -1
	s_mov_b64 s[72:73], -1
	s_mov_b64 s[74:75], -1
	s_mov_b64 s[76:77], -1
	s_mov_b64 s[78:79], -1
	s_mov_b64 s[80:81], -1
	s_mov_b64 s[82:83], -1
	s_mov_b64 s[84:85], -1
	s_mov_b64 s[86:87], -1
	s_mov_b64 s[88:89], -1
	s_mov_b64 s[90:91], -1
	s_branch .Lhgl_mdone_a
.Lhgl_mslow_a:
	s_add_i32 s93, s92, 1
	s_cmp_gt_i32 s18, s93
	s_cselect_b64 s[64:65], -1, 0
	s_add_i32 s93, s92, 2
	s_cmp_gt_i32 s18, s93
	s_cselect_b64 s[66:67], -1, 0
	s_add_i32 s93, s92, 3
	s_cmp_gt_i32 s18, s93
	s_cselect_b64 s[68:69], -1, 0
	s_add_i32 s93, s92, 4
	s_cmp_gt_i32 s18, s93
	s_cselect_b64 s[70:71], -1, 0
	s_add_i32 s93, s92, 5
	s_cmp_gt_i32 s18, s93
	s_cselect_b64 s[72:73], -1, 0
	s_add_i32 s93, s92, 6
	s_cmp_gt_i32 s18, s93
	s_cselect_b64 s[74:75], -1, 0
	s_add_i32 s93, s92, 7
	s_cmp_gt_i32 s18, s93
	s_cselect_b64 s[76:77], -1, 0
	s_add_i32 s93, s92, 8
	s_cmp_gt_i32 s18, s93
	s_cselect_b64 s[78:79], -1, 0
	s_add_i32 s93, s92, 9
	s_cmp_gt_i32 s18, s93
	s_cselect_b64 s[80:81], -1, 0
	s_add_i32 s93, s92, 10
	s_cmp_gt_i32 s18, s93
	s_cselect_b64 s[82:83], -1, 0
	s_add_i32 s93, s92, 11
	s_cmp_gt_i32 s18, s93
	s_cselect_b64 s[84:85], -1, 0
	s_add_i32 s93, s92, 12
	s_cmp_gt_i32 s18, s93
	s_cselect_b64 s[86:87], -1, 0
	s_add_i32 s93, s92, 13
	s_cmp_gt_i32 s18, s93
	s_cselect_b64 s[88:89], -1, 0
	s_add_i32 s93, s92, 14
	s_cmp_gt_i32 s18, s93
	s_cselect_b64 s[90:91], -1, 0
.Lhgl_mdone_a:
	s_cmp_lg_u64 s[96:97], 0
	s_cbranch_scc0 .Lhgl_so_a
	v_add_u32_e32 v64, 0x2000, v64
	global_load_dword v199, v64, s[98:99]
	global_load_ushort v200, v65, s[100:101]
	v_add_u32_e32 v64, 0x4000, v64
	v_add_u32_e32 v65, 0x2000, v65
	global_load_dword v205, v64, s[98:99]
	global_load_ushort v206, v65, s[100:101]
	v_add_u32_e32 v64, 0x2000, v64
	v_add_u32_e32 v65, 0x2000, v65
	global_load_ushort v207, v65, s[10:11] offset:-4096 nt
	global_load_dword v209, v64, s[98:99]
	global_load_ushort v210, v65, s[100:101] offset:-4096
	v_add_u32_e32 v64, 0x2000, v64
	global_load_dword v211, v64, s[98:99]
	global_load_ushort v212, v65, s[100:101]
	v_add_u32_e32 v64, 0x2000, v64
	v_add_u32_e32 v65, 0x2000, v65
	global_load_ushort v213, v65, s[10:11] offset:-4096 nt
	global_load_dword v215, v64, s[98:99]
	global_load_ushort v216, v65, s[100:101] offset:-4096
	v_add_u32_e32 v64, 0x2000, v64
	global_load_ushort v214, v65, s[10:11] nt
	global_load_dword v217, v64, s[98:99]
	global_load_ushort v218, v65, s[100:101]
	v_add_u32_e32 v64, 0x2000, v64
	v_add_u32_e32 v65, 0x2000, v65
	global_load_ushort v219, v65, s[10:11] offset:-4096 nt
	global_load_dword v221, v64, s[98:99]
	global_load_ushort v222, v65, s[100:101] offset:-4096
	v_add_u32_e32 v64, 0x2000, v64
	global_load_ushort v220, v65, s[10:11] nt
	global_load_dword v223, v64, s[98:99]
	global_load_ushort v224, v65, s[100:101]
	v_add_u32_e32 v64, 0x2000, v64
	v_add_u32_e32 v65, 0x2000, v65
	global_load_ushort v225, v65, s[10:11] offset:-4096 nt
	global_load_dword v227, v64, s[98:99]
	global_load_ushort v228, v65, s[100:101] offset:-4096
	v_add_u32_e32 v64, 0x2000, v64
	global_load_ushort v226, v65, s[10:11] nt
	global_load_dword v229, v64, s[98:99]
	global_load_ushort v230, v65, s[100:101]
	v_add_u32_e32 v64, 0x2000, v64
	v_add_u32_e32 v65, 0x2000, v65
	global_load_ushort v231, v65, s[10:11] offset:-4096 nt
	global_load_dword v233, v64, s[98:99]
	global_load_ushort v234, v65, s[100:101] offset:-4096
	v_add_u32_e32 v64, 0x2000, v64
	global_load_ushort v232, v65, s[10:11] nt
	global_load_dword v235, v64, s[98:99]
	global_load_ushort v236, v65, s[100:101]
	v_add_u32_e32 v64, 0x2000, v64
	v_add_u32_e32 v65, 0x2000, v65
	global_load_ushort v237, v65, s[10:11] offset:-4096 nt
	global_load_dword v238, v64, s[98:99]
	v_add_u32_e32 v64, 0x2000, v64
	global_load_ushort v239, v65, s[10:11] nt
	global_load_dword v242, v64, s[98:99]
	global_load_ushort v241, v65, s[100:101]
	s_branch .Lhgl_done_a
.Lhgl_so_a:
	v_add_u32_e32 v64, 0x2000, v64
	global_load_dword v199, v64, s[98:99]
	global_load_ushort v200, v65, s[100:101]
	v_add_u32_e32 v64, 0x4000, v64
	v_add_u32_e32 v65, 0x2000, v65
	global_load_dword v205, v64, s[98:99]
	global_load_ushort v206, v65, s[100:101]
	v_add_u32_e32 v64, 0x2000, v64
	v_add_u32_e32 v65, 0x2000, v65
	global_load_dword v209, v64, s[98:99]
	global_load_ushort v210, v65, s[100:101] offset:-4096
	v_add_u32_e32 v64, 0x2000, v64
	global_load_dword v211, v64, s[98:99]
	global_load_ushort v212, v65, s[100:101]
	v_add_u32_e32 v64, 0x2000, v64
	v_add_u32_e32 v65, 0x2000, v65
	global_load_dword v215, v64, s[98:99]
	global_load_ushort v216, v65, s[100:101] offset:-4096
	v_add_u32_e32 v64, 0x2000, v64
	global_load_dword v217, v64, s[98:99]
	global_load_ushort v218, v65, s[100:101]
	v_add_u32_e32 v64, 0x2000, v64
	v_add_u32_e32 v65, 0x2000, v65
	global_load_dword v221, v64, s[98:99]
	global_load_ushort v222, v65, s[100:101] offset:-4096
	v_add_u32_e32 v64, 0x2000, v64
	global_load_dword v223, v64, s[98:99]
	global_load_ushort v224, v65, s[100:101]
	v_add_u32_e32 v64, 0x2000, v64
	v_add_u32_e32 v65, 0x2000, v65
	global_load_dword v227, v64, s[98:99]
	global_load_ushort v228, v65, s[100:101] offset:-4096
	v_add_u32_e32 v64, 0x2000, v64
	global_load_dword v229, v64, s[98:99]
	global_load_ushort v230, v65, s[100:101]
	v_add_u32_e32 v64, 0x2000, v64
	v_add_u32_e32 v65, 0x2000, v65
	global_load_dword v233, v64, s[98:99]
	global_load_ushort v234, v65, s[100:101] offset:-4096
	v_add_u32_e32 v64, 0x2000, v64
	global_load_dword v235, v64, s[98:99]
	global_load_ushort v236, v65, s[100:101]
	v_add_u32_e32 v64, 0x2000, v64
	global_load_dword v238, v64, s[98:99]
	v_add_u32_e32 v64, 0x2000, v64
	v_add_u32_e32 v65, 0x2000, v65
	global_load_dword v242, v64, s[98:99]
	global_load_ushort v241, v65, s[100:101]

.LBB0_392:
	ds_write_b128 v178, v[34:37] offset:34816
	ds_write_b128 v178, v[38:41] offset:34832
	ds_write_b128 v178, v[122:125] offset:53248
	ds_write_b128 v178, v[118:121] offset:53264
	s_and_saveexec_b64 s[0:1], s[40:41]
	ds_write_b32 v162, v42
	s_or_b64 exec, exec, s[0:1]
	s_lshl_b32 s93, s92, 11
	v_or_b32_e32 v35, s93, v158
	v_lshlrev_b32_e32 v34, 2, v35
	v_lshlrev_b32_e32 v35, 1, v35
	v_add_u32_e32 v35, 0x1000, v35
	s_add_i32 s93, s92, 15
	s_cmp_lt_i32 s93, s18
	s_cbranch_scc0 .Lhgl_mslow_b
	s_mov_b64 s[62:63], -1
	s_branch .Lhgl_mdone_b
.Lhgl_mslow_b:
	s_add_i32 s93, s92, 0
	s_cmp_gt_i32 s18, s93
	s_cselect_b64 s[62:63], -1, 0
.Lhgl_mdone_b:
	s_cmp_lg_u64 s[96:97], 0
	s_cbranch_scc0 .Lhgl_so_b
	global_load_ushort v195, v35, s[10:11] offset:-4096 nt
	global_load_dword v197, v34, s[98:99]
	global_load_ushort v198, v35, s[100:101] offset:-4096
	global_load_ushort v196, v35, s[10:11] nt
	v_add_u32_e32 v34, 0x4000, v34
	v_add_u32_e32 v35, 0x2000, v35
	global_load_ushort v201, v35, s[10:11] offset:-4096 nt
	global_load_dword v203, v34, s[98:99]
	global_load_ushort v204, v35, s[100:101] offset:-4096
	global_load_ushort v202, v35, s[10:11] nt
	v_add_u32_e32 v35, 0x2000, v35
	global_load_ushort v208, v35, s[10:11] nt
	v_add_u32_e32 v35, 0xa000, v35
	global_load_ushort v240, v35, s[100:101] offset:-4096
	s_branch .Lhgl_done_b
.Lhgl_so_b:
	v_mov_b32_e32 v195, 0
	v_mov_b32_e32 v196, 0
	v_mov_b32_e32 v201, 0
	v_mov_b32_e32 v202, 0
	v_mov_b32_e32 v207, 0
	v_mov_b32_e32 v208, 0
	v_mov_b32_e32 v213, 0
	v_mov_b32_e32 v214, 0
	v_mov_b32_e32 v219, 0
	v_mov_b32_e32 v220, 0
	v_mov_b32_e32 v225, 0
	v_mov_b32_e32 v226, 0
	v_mov_b32_e32 v231, 0
	v_mov_b32_e32 v232, 0
	v_mov_b32_e32 v237, 0
	v_mov_b32_e32 v239, 0
	global_load_dword v197, v34, s[98:99]
	global_load_ushort v198, v35, s[100:101] offset:-4096
	v_add_u32_e32 v34, 0x4000, v34
	v_add_u32_e32 v35, 0x2000, v35
	global_load_dword v203, v34, s[98:99]
	global_load_ushort v204, v35, s[100:101] offset:-4096
	v_add_u32_e32 v35, 0xc000, v35
	global_load_ushort v240, v35, s[100:101] offset:-4096
.Lhgl_done_b:
	s_add_i32 s93, s92, 15
	s_cmp_gt_i32 s18, s93
	s_cselect_b64 s[92:93], -1, 0
	s_add_i32 s12, s24, 1
	s_cmp_ge_u32 s12, s5
	s_cselect_b64 s[0:1], -1, 0
	s_cmp_lt_u32 s12, s5
	s_cselect_b32 s10, s12, s24
	s_waitcnt lgkmcnt(0)
	s_barrier
	ds_read_b128 v[122:125], v179
	s_and_b64 vcc, exec, s[36:37]
	s_mov_b64 s[10:11], -1
	s_cbranch_vccnz .LBB0_432
	v_lshl_add_u32 v34, s24, 6, v163
	v_cmp_gt_i32_e32 vcc, s18, v34
	v_add_u32_e32 v34, s23, v34
	v_mov_b32_e32 v134, 0
	v_cndmask_b32_e32 v34, v164, v34, vcc
	v_ashrrev_i32_e32 v35, 31, v34
	v_lshlrev_b64 v[152:153], 11, v[34:35]
	v_or_b32_e32 v152, v152, v150
	v_lshl_add_u64 v[34:35], v[152:153], 1, s[14:15]
	global_load_dwordx4 v[118:121], v[34:35], off offset:16 nt
	global_load_dwordx4 v[126:129], v[34:35], off nt
	ds_read_b128 v[50:53], v180
	ds_read_b128 v[46:49], v180 offset:64
	ds_read_b128 v[42:45], v180 offset:128
	ds_read_b128 v[38:41], v180 offset:192
	ds_read_b128 v[34:37], v181
	ds_read_b128 v[54:57], v181 offset:64
	ds_read_b128 v[58:61], v181 offset:4416
	s_waitcnt lgkmcnt(2)
	v_mfma_f32_16x16x32_bf16 v[34:37], v[50:53], v[34:37], 0
	ds_read_b128 v[62:65], v181 offset:8768
	v_mov_b32_e32 v135, 0
	ds_read_b128 v[130:133], v181 offset:13120
	s_waitcnt lgkmcnt(3)
	v_mfma_f32_16x16x32_bf16 v[34:37], v[46:49], v[54:57], v[34:37]
	ds_read_b128 v[54:57], v181 offset:128
	s_waitcnt lgkmcnt(0)
	v_mfma_f32_16x16x32_bf16 v[34:37], v[42:45], v[54:57], v[34:37]
	ds_read_b128 v[54:57], v181 offset:192
	s_waitcnt lgkmcnt(0)
	v_mfma_f32_16x16x32_bf16 v[34:37], v[38:41], v[54:57], v[34:37]
	ds_read_b128 v[54:57], v181 offset:4352
	s_waitcnt lgkmcnt(0)
	v_mfma_f32_16x16x32_bf16 v[54:57], v[50:53], v[54:57], 0
	v_mfma_f32_16x16x32_bf16 v[54:57], v[46:49], v[58:61], v[54:57]
	ds_read_b128 v[58:61], v181 offset:4480
	s_waitcnt lgkmcnt(0)
	v_mfma_f32_16x16x32_bf16 v[54:57], v[42:45], v[58:61], v[54:57]
	ds_read_b128 v[58:61], v181 offset:4544
	s_waitcnt lgkmcnt(0)
	v_mfma_f32_16x16x32_bf16 v[54:57], v[38:41], v[58:61], v[54:57]
	ds_read_b128 v[58:61], v181 offset:8704
	s_waitcnt lgkmcnt(0)
	v_mfma_f32_16x16x32_bf16 v[58:61], v[50:53], v[58:61], 0
	v_mfma_f32_16x16x32_bf16 v[58:61], v[46:49], v[62:65], v[58:61]
	ds_read_b128 v[62:65], v181 offset:8832
	s_waitcnt lgkmcnt(0)
	v_mfma_f32_16x16x32_bf16 v[58:61], v[42:45], v[62:65], v[58:61]
	ds_read_b128 v[62:65], v181 offset:8896
	s_waitcnt lgkmcnt(0)
	v_mfma_f32_16x16x32_bf16 v[58:61], v[38:41], v[62:65], v[58:61]
	ds_read_b128 v[62:65], v181 offset:13056
	s_waitcnt lgkmcnt(0)
	v_mfma_f32_16x16x32_bf16 v[62:65], v[50:53], v[62:65], 0
	v_mfma_f32_16x16x32_bf16 v[62:65], v[46:49], v[130:133], v[62:65]
	ds_read_b128 v[130:133], v181 offset:13184
	s_waitcnt lgkmcnt(0)
	v_mfma_f32_16x16x32_bf16 v[62:65], v[42:45], v[130:133], v[62:65]
	ds_read_b128 v[130:133], v181 offset:13248
	s_waitcnt lgkmcnt(0)
	v_mfma_f32_16x16x32_bf16 v[62:65], v[38:41], v[130:133], v[62:65]
	v_mov_b32_e32 v130, 0
	v_mov_b32_e32 v132, 0
	v_mov_b32_e32 v133, 0
	s_and_saveexec_b64 vcc, s[42:43]
	s_cbranch_execz .LBB0_429
	ds_read_b128 v[132:135], v194 offset:17408
	ds_read_b128 v[136:139], v194 offset:17472
	s_waitcnt lgkmcnt(1)
	v_mfma_f32_16x16x32_bf16 v[132:135], v[50:53], v[132:135], 0
	s_waitcnt lgkmcnt(0)
	v_mfma_f32_16x16x32_bf16 v[132:135], v[46:49], v[136:139], v[132:135]
	ds_read_b128 v[136:139], v194 offset:17536
	s_waitcnt lgkmcnt(0)
	v_mfma_f32_16x16x32_bf16 v[132:135], v[42:45], v[136:139], v[132:135]
	ds_read_b128 v[136:139], v194 offset:17600
	s_waitcnt lgkmcnt(0)
	v_mfma_f32_16x16x32_bf16 v[132:135], v[38:41], v[136:139], v[132:135]

.LBB0_432:
	s_and_b64 vcc, exec, s[10:11]
	s_cbranch_vccz .LBB0_434
	v_add_u32_e32 v42, v167, v165
	v_add_u32_e32 v43, v166, v176
	ds_read_b128 v[34:37], v42 offset:34816
	ds_read_b128 v[44:47], v43 offset:53248
	ds_read_b128 v[48:51], v43 offset:55552
	ds_read_b128 v[52:55], v43 offset:57856
	ds_read_b128 v[56:59], v43 offset:60160
	ds_read_b128 v[60:63], v43 offset:62464
	ds_read_b128 v[126:129], v43 offset:64768
	ds_read_b128 v[130:133], v191 offset:13824
	ds_read_b128 v[134:137], v191 offset:16128
	ds_read_b128 v[38:41], v42 offset:34880
	s_waitcnt lgkmcnt(8)
	v_mfma_f32_16x16x32_bf16 v[2:5], v[34:37], v[44:47], v[2:5]
	ds_read_b128 v[44:47], v43 offset:53312
	s_waitcnt lgkmcnt(8)
	v_mfma_f32_16x16x32_bf16 v[6:9], v[34:37], v[48:51], v[6:9]
	ds_read_b128 v[48:51], v43 offset:55616
	s_waitcnt lgkmcnt(8)
	v_mfma_f32_16x16x32_bf16 v[10:13], v[34:37], v[52:55], v[10:13]
	ds_read_b128 v[52:55], v43 offset:57920
	s_waitcnt lgkmcnt(8)
	v_mfma_f32_16x16x32_bf16 v[14:17], v[34:37], v[56:59], v[14:17]
	ds_read_b128 v[56:59], v43 offset:60224
	s_waitcnt lgkmcnt(8)
	v_mfma_f32_16x16x32_bf16 v[18:21], v[34:37], v[60:63], v[18:21]
	ds_read_b128 v[60:63], v43 offset:62528
	s_waitcnt lgkmcnt(8)
	v_mfma_f32_16x16x32_bf16 v[22:25], v[34:37], v[126:129], v[22:25]
	ds_read_b128 v[126:129], v43 offset:64832
	s_waitcnt lgkmcnt(8)
	v_mfma_f32_16x16x32_bf16 v[26:29], v[34:37], v[130:133], v[26:29]
	ds_read_b128 v[130:133], v192 offset:13824
	s_waitcnt lgkmcnt(8)
	v_mfma_f32_16x16x32_bf16 v[30:33], v[34:37], v[134:137], v[30:33]
	ds_read_b128 v[134:137], v192 offset:16128
	s_waitcnt lgkmcnt(7)
	v_mfma_f32_16x16x32_bf16 v[2:5], v[38:41], v[44:47], v[2:5]
	s_waitcnt lgkmcnt(6)
	v_mfma_f32_16x16x32_bf16 v[6:9], v[38:41], v[48:51], v[6:9]
	s_waitcnt lgkmcnt(5)
	v_mfma_f32_16x16x32_bf16 v[10:13], v[38:41], v[52:55], v[10:13]
	s_waitcnt lgkmcnt(4)
	v_mfma_f32_16x16x32_bf16 v[14:17], v[38:41], v[56:59], v[14:17]
	s_waitcnt lgkmcnt(3)
	v_mfma_f32_16x16x32_bf16 v[18:21], v[38:41], v[60:63], v[18:21]
	s_waitcnt lgkmcnt(2)
	v_mfma_f32_16x16x32_bf16 v[22:25], v[38:41], v[126:129], v[22:25]
	s_waitcnt lgkmcnt(1)
	v_mfma_f32_16x16x32_bf16 v[26:29], v[38:41], v[130:133], v[26:29]
	s_waitcnt lgkmcnt(0)
	v_mfma_f32_16x16x32_bf16 v[30:33], v[38:41], v[134:137], v[30:33]
	v_pk_mul_f32 v[34:35], v[122:123], v[2:3]
	v_mul_f32_e64 v36, v124, v4
	v_mul_f32_e64 v37, v125, v5
	v_pk_mul_f32 v[38:39], v[122:123], v[6:7]
	v_pk_mul_f32 v[40:41], v[124:125], v[8:9]
	v_pk_mul_f32 v[42:43], v[122:123], v[10:11]
	v_pk_mul_f32 v[44:45], v[124:125], v[12:13]
	v_pk_mul_f32 v[46:47], v[122:123], v[14:15]
	v_pk_mul_f32 v[48:49], v[124:125], v[16:17]
	v_pk_mul_f32 v[50:51], v[122:123], v[18:19]
	v_pk_mul_f32 v[52:53], v[124:125], v[20:21]
	v_pk_mul_f32 v[54:55], v[122:123], v[22:23]
	v_pk_mul_f32 v[56:57], v[124:125], v[24:25]
	v_pk_mul_f32 v[58:59], v[122:123], v[26:27]
	v_pk_mul_f32 v[60:61], v[124:125], v[28:29]
	v_pk_mul_f32 v[62:63], v[122:123], v[30:31]
	v_pk_mul_f32 v[64:65], v[124:125], v[32:33]

.LBB0_1244:
	v_ashrrev_i32_e32 v163, 6, v208
	v_lshl_add_u32 v52, s16, 3, v163
	v_readlane_b32 s68, v255, 3
	v_ashrrev_i32_e32 v53, 31, v52
	v_readlane_b32 s74, v255, 9
	v_readlane_b32 s75, v255, 10
	s_lshl_b32 s21, s34, 3
	v_and_b32_e32 v206, 15, v208
	v_lshl_add_u64 v[54:55], v[52:53], 2, s[74:75]
	global_load_dword v207, v[54:55], off
	s_addk_i32 s21, 0x2040
	s_mov_b64 s[16:17], -1
	s_and_b64 vcc, exec, s[0:1]
	v_readlane_b32 s69, v255, 4
	v_readlane_b32 s70, v255, 5
	v_readlane_b32 s71, v255, 6
	v_readlane_b32 s72, v255, 7
	v_readlane_b32 s73, v255, 8
	v_readlane_b32 s76, v255, 11
	v_readlane_b32 s77, v255, 12
	v_readlane_b32 s78, v255, 13
	v_readlane_b32 s79, v255, 14
	v_readlane_b32 s80, v255, 15
	v_readlane_b32 s81, v255, 16
	v_readlane_b32 s82, v255, 17
	v_readlane_b32 s83, v255, 18
	s_cbranch_vccz .LBB0_1246
	v_cmp_gt_u32_e64 s[12:13], 8, v206
	s_mov_b64 s[16:17], 0
	s_nop 0
	v_cndmask_b32_e64 v50, 0, v206, s[12:13]
	v_add_u32_e32 v54, s21, v50

.LBB0_1284:
	s_waitcnt vmcnt(0)
	s_sub_i32 s0, 0x80, s20
	s_max_i32 s17, s0, 0
	s_and_b64 s[0:1], s[66:67], exec
	v_bfe_u32 v50, v208, 4, 2
	s_cselect_b32 s12, s17, 0
	v_add_u32_e32 v53, 1, v206
	v_lshlrev_b32_e32 v52, 2, v50
	v_max_u32_e32 v53, s12, v53
	v_cmp_ge_u32_e32 vcc, v52, v53
	v_or_b32_e32 v70, 1, v52
	v_or_b32_e32 v71, 2, v52
	v_cndmask_b32_e32 v84, v159, v78, vcc
	v_cmp_ge_u32_e32 vcc, v70, v53
	v_or_b32_e32 v151, 16, v52
	v_or_b32_e32 v152, 17, v52
	v_cndmask_b32_e32 v82, v159, v79, vcc
	v_cmp_ge_u32_e32 vcc, v71, v53
	v_or_b32_e32 v71, 3, v52
	v_or_b32_e32 v153, 18, v52
	v_cndmask_b32_e32 v83, v159, v80, vcc
	v_cmp_ge_u32_e32 vcc, v71, v53
	v_max3_f32 v70, v84, s25, v82
	v_or_b32_e32 v208, 19, v52
	v_cndmask_b32_e32 v80, v159, v81, vcc
	v_cmp_ge_u32_e32 vcc, v151, v53
	v_max3_f32 v70, v70, v83, v80
	s_cmp_gt_u32 s12, 32
	v_cndmask_b32_e32 v81, v159, v146, vcc
	v_cmp_ge_u32_e32 vcc, v152, v53
	s_cselect_b64 s[0:1], -1, 0
	s_cmp_lt_u32 s12, 33
	v_cndmask_b32_e32 v71, v159, v147, vcc
	v_cmp_ge_u32_e32 vcc, v153, v53
	v_max3_f32 v73, v70, v81, v71
	s_mov_b64 s[12:13], -1
	v_cndmask_b32_e32 v72, v159, v148, vcc
	v_cmp_ge_u32_e32 vcc, v208, v53
	v_mov_b32_e32 v78, v96
	v_mov_b32_e32 v79, v95
	v_cndmask_b32_e32 v70, v159, v149, vcc
	v_max3_f32 v146, v73, v72, v70
	v_mov_b32_e32 v73, v97
	v_mov_b32_e32 v85, v94
	s_cbranch_scc1 .LBB0_1286
	v_or_b32_e32 v73, 32, v52
	v_cmp_ge_u32_e32 vcc, v73, v53
	v_or_b32_e32 v73, 33, v52
	s_mov_b64 s[12:13], 0
	v_cndmask_b32_e32 v85, v159, v94, vcc
	v_cmp_ge_u32_e32 vcc, v73, v53
	v_or_b32_e32 v73, 34, v52
	s_nop 0
	v_cndmask_b32_e32 v79, v159, v95, vcc
	v_cmp_ge_u32_e32 vcc, v73, v53
	v_or_b32_e32 v73, 35, v52
	v_max3_f32 v147, v146, v85, v79
	v_cndmask_b32_e32 v78, v159, v96, vcc
	v_cmp_ge_u32_e32 vcc, v73, v53
	s_nop 1
	v_cndmask_b32_e32 v73, v159, v97, vcc
	v_max3_f32 v147, v147, v78, v73

.LBB0_1459:
	v_add_u32_e32 v50, v50, v194
	v_lshl_add_u64 v[52:53], v[190:191], 1, s[30:31]
	v_mov_b32_e32 v195, v51
	s_waitcnt lgkmcnt(0)
	v_lshl_add_u64 v[70:71], v[52:53], 0, v[194:195]
	v_mad_u32_u24 v52, v161, s22, v50
	ds_read_b128 v[72:75], v52
	v_lshlrev_b32_e32 v53, 16, v66
	v_and_b32_e32 v66, 0xffff0000, v66
	s_and_b64 s[0:1], s[66:67], s[74:75]
	s_xor_b64 s[10:11], s[0:1], -1
	s_waitcnt lgkmcnt(0)
	v_lshlrev_b32_e32 v52, 16, v72
	v_mul_f32_e32 v52, v53, v52
	v_and_b32_e32 v53, 0xffff0000, v72
	v_mul_f32_e32 v53, v66, v53
	v_cvt_pk_bf16_f32 v66, v52, v53
	v_lshlrev_b32_e32 v52, 16, v73
	v_lshlrev_b32_e32 v53, 16, v67
	v_mul_f32_e32 v52, v53, v52
	v_and_b32_e32 v53, 0xffff0000, v73
	v_and_b32_e32 v67, 0xffff0000, v67
	v_mul_f32_e32 v53, v67, v53
	v_cvt_pk_bf16_f32 v67, v52, v53
	v_lshlrev_b32_e32 v52, 16, v74
	v_lshlrev_b32_e32 v53, 16, v68
	v_mul_f32_e32 v52, v53, v52
	v_and_b32_e32 v53, 0xffff0000, v74
	v_and_b32_e32 v68, 0xffff0000, v68
	v_mul_f32_e32 v53, v68, v53
	v_cvt_pk_bf16_f32 v68, v52, v53
	v_lshlrev_b32_e32 v52, 16, v75
	v_lshlrev_b32_e32 v53, 16, v69
	v_mul_f32_e32 v52, v53, v52
	v_and_b32_e32 v53, 0xffff0000, v75
	v_and_b32_e32 v69, 0xffff0000, v69
	v_mul_f32_e32 v53, v69, v53
	v_cvt_pk_bf16_f32 v69, v52, v53
	s_and_saveexec_b64 s[0:1], s[10:11]
	s_cbranch_execz .LBB0_1461
	v_lshl_add_u64 v[52:53], v[70:71], 0, v[192:193]
	global_store_dwordx4 v[52:53], v[66:69], off
.LBB0_1461:
	s_or_b64 exec, exec, s[0:1]
	v_mul_u32_u24_e32 v52, 0x90, v161
	v_add_u32_e32 v50, v50, v52
	ds_read_b128 v[66:69], v50 offset:1152
	v_lshlrev_b32_e32 v52, 16, v62
	v_and_b32_e32 v53, 0xffff0000, v62
	s_and_b64 s[10:11], s[66:67], s[72:73]
	s_waitcnt lgkmcnt(0)
	v_lshlrev_b32_e32 v62, 16, v66
	v_and_b32_e32 v66, 0xffff0000, v66
	v_mul_f32_e32 v52, v52, v62
	v_mul_f32_e32 v53, v53, v66
	v_cvt_pk_bf16_f32 v62, v52, v53
	v_lshlrev_b32_e32 v52, 16, v67
	v_lshlrev_b32_e32 v53, 16, v63
	v_mul_f32_e32 v52, v53, v52
	v_and_b32_e32 v53, 0xffff0000, v67
	v_and_b32_e32 v63, 0xffff0000, v63
	v_mul_f32_e32 v53, v63, v53
	v_cvt_pk_bf16_f32 v63, v52, v53
	v_lshlrev_b32_e32 v52, 16, v68
	v_lshlrev_b32_e32 v53, 16, v64
	v_mul_f32_e32 v52, v53, v52
	v_and_b32_e32 v53, 0xffff0000, v68
	v_and_b32_e32 v64, 0xffff0000, v64
	v_mul_f32_e32 v53, v64, v53
	v_cvt_pk_bf16_f32 v64, v52, v53
	v_lshlrev_b32_e32 v52, 16, v69
	v_lshlrev_b32_e32 v53, 16, v65
	v_mul_f32_e32 v52, v53, v52
	v_and_b32_e32 v53, 0xffff0000, v69
	v_and_b32_e32 v65, 0xffff0000, v65
	v_mul_f32_e32 v53, v65, v53
	v_cvt_pk_bf16_f32 v65, v52, v53
	s_and_saveexec_b64 s[0:1], s[10:11]
	s_cbranch_execz .LBB0_1463
	v_lshl_add_u64 v[52:53], v[70:71], 0, v[188:189]
	global_store_dwordx4 v[52:53], v[62:65], off
.LBB0_1463:
	s_or_b64 exec, exec, s[0:1]
	s_and_b64 vcc, exec, s[76:77]
	s_cbranch_vccnz .LBB0_1233
	ds_read_b128 v[62:65], v50 offset:2304
	v_lshlrev_b32_e32 v52, 16, v58
	v_and_b32_e32 v53, 0xffff0000, v58
	s_waitcnt lgkmcnt(0)
	v_lshlrev_b32_e32 v58, 16, v62
	v_and_b32_e32 v62, 0xffff0000, v62
	v_mul_f32_e32 v52, v52, v58
	v_mul_f32_e32 v53, v53, v62
	v_cvt_pk_bf16_f32 v58, v52, v53
	v_lshlrev_b32_e32 v52, 16, v63
	v_lshlrev_b32_e32 v53, 16, v59
	v_mul_f32_e32 v52, v53, v52
	v_and_b32_e32 v53, 0xffff0000, v63
	v_and_b32_e32 v59, 0xffff0000, v59
	v_mul_f32_e32 v53, v59, v53
	v_cvt_pk_bf16_f32 v59, v52, v53
	v_lshlrev_b32_e32 v52, 16, v64
	v_lshlrev_b32_e32 v53, 16, v60
	v_mul_f32_e32 v52, v53, v52
	v_and_b32_e32 v53, 0xffff0000, v64
	v_and_b32_e32 v60, 0xffff0000, v60
	v_mul_f32_e32 v53, v60, v53
	v_cvt_pk_bf16_f32 v60, v52, v53
	v_lshlrev_b32_e32 v52, 16, v65
	v_lshlrev_b32_e32 v53, 16, v61
	v_mul_f32_e32 v52, v53, v52
	v_and_b32_e32 v53, 0xffff0000, v65
	v_and_b32_e32 v61, 0xffff0000, v61
	v_mul_f32_e32 v53, v61, v53
	v_cvt_pk_bf16_f32 v61, v52, v53
	s_and_saveexec_b64 s[0:1], s[70:71]
	s_cbranch_execz .LBB0_1466
	v_lshl_add_u64 v[52:53], v[70:71], 0, v[186:187]
	global_store_dwordx4 v[52:53], v[58:61], off
.LBB0_1466:
	s_or_b64 exec, exec, s[0:1]
	ds_read_b128 v[58:61], v50 offset:3456
	v_lshlrev_b32_e32 v50, 16, v54
	v_and_b32_e32 v52, 0xffff0000, v54
	s_waitcnt lgkmcnt(0)
	v_lshlrev_b32_e32 v53, 16, v58
	v_and_b32_e32 v54, 0xffff0000, v58
	v_mul_f32_e32 v50, v50, v53
	v_mul_f32_e32 v52, v52, v54
	v_cvt_pk_bf16_f32 v52, v50, v52
	v_lshlrev_b32_e32 v50, 16, v59
	v_lshlrev_b32_e32 v53, 16, v55
	v_mul_f32_e32 v50, v53, v50
	v_and_b32_e32 v53, 0xffff0000, v59
	v_and_b32_e32 v54, 0xffff0000, v55
	v_mul_f32_e32 v53, v54, v53
	v_cvt_pk_bf16_f32 v53, v50, v53
	v_lshlrev_b32_e32 v50, 16, v60
	v_lshlrev_b32_e32 v54, 16, v56
	v_mul_f32_e32 v50, v54, v50
	v_and_b32_e32 v54, 0xffff0000, v60
	v_and_b32_e32 v55, 0xffff0000, v56
	v_mul_f32_e32 v54, v55, v54
	v_cvt_pk_bf16_f32 v54, v50, v54
	v_lshlrev_b32_e32 v50, 16, v61
	v_lshlrev_b32_e32 v55, 16, v57
	v_mul_f32_e32 v50, v55, v50
	v_and_b32_e32 v55, 0xffff0000, v61
	v_and_b32_e32 v56, 0xffff0000, v57
	v_mul_f32_e32 v55, v56, v55
	v_cvt_pk_bf16_f32 v55, v50, v55
	s_and_saveexec_b64 s[0:1], s[68:69]
	s_cbranch_execz .LBB0_1232
	v_lshl_add_u64 v[56:57], v[70:71], 0, v[184:185]
	global_store_dwordx4 v[56:57], v[52:55], off
	s_branch .LBB0_1232

.LBB0_1679:
	v_cmp_lt_u32_e32 vcc, s11, v173
	s_and_saveexec_b64 s[6:7], vcc
	s_xor_b64 s[6:7], exec, s[6:7]
	s_cbranch_execz .LBB0_1681
	v_add_u32_e32 v0, 0xffffe000, v173
	v_lshlrev_b64 v[122:123], 13, v[0:1]
	v_lshl_add_u64 v[122:123], v[92:93], 0, v[122:123]
	s_waitcnt lgkmcnt(0)
	v_add_co_u32_e32 v182, vcc, s12, v122
	s_nop 1
	v_addc_co_u32_e32 v183, vcc, 0, v123, vcc
	v_add_co_u32_e32 v184, vcc, s14, v122
	s_nop 1
	v_addc_co_u32_e32 v185, vcc, 0, v123, vcc
	v_add_co_u32_e32 v186, vcc, s16, v122
	s_nop 1
	v_addc_co_u32_e32 v187, vcc, 0, v123, vcc
	v_add_co_u32_e32 v68, vcc, s18, v122
	s_nop 1
	v_addc_co_u32_e32 v69, vcc, 0, v123, vcc
	global_load_dwordx4 v[188:191], v[182:183], off offset:-4096 nt
	global_load_dwordx4 v[192:195], v[182:183], off offset:-3072 nt
	global_load_dwordx4 v[196:199], v[182:183], off offset:-2048 nt
	global_load_dwordx4 v[200:203], v[182:183], off offset:-1024 nt
	global_load_dwordx4 v[204:207], v[182:183], off nt
	global_load_dwordx4 v[208:211], v[182:183], off offset:1024 nt
	global_load_dwordx4 v[212:215], v[182:183], off offset:2048 nt
	global_load_dwordx4 v[216:219], v[182:183], off offset:3072 nt
	global_load_dwordx4 v[220:223], v[184:185], off offset:-4096 nt
	global_load_dwordx4 v[224:227], v[184:185], off offset:-3072 nt
	global_load_dwordx4 v[228:231], v[184:185], off offset:-2048 nt
	global_load_dwordx4 v[232:235], v[184:185], off offset:-1024 nt
	global_load_dwordx4 v[236:239], v[184:185], off nt
	global_load_dwordx4 v[240:243], v[184:185], off offset:1024 nt
	global_load_dwordx4 v[244:247], v[184:185], off offset:2048 nt
	global_load_dwordx4 v[248:251], v[184:185], off offset:3072 nt
	s_waitcnt vmcnt(15)
	v_pk_fma_f32 v[128:129], v[84:85], s[4:5], v[190:191] op_sel_hi:[1,0,1]
	v_pk_fma_f32 v[130:131], v[86:87], s[4:5], v[188:189] op_sel_hi:[1,0,1]
	global_load_dwordx4 v[188:191], v[186:187], off offset:-4096 nt
	s_waitcnt vmcnt(15)
	v_pk_fma_f32 v[132:133], v[88:89], s[4:5], v[194:195] op_sel_hi:[1,0,1]
	v_pk_fma_f32 v[134:135], v[90:91], s[4:5], v[192:193] op_sel_hi:[1,0,1]
	global_load_dwordx4 v[192:195], v[186:187], off offset:-3072 nt
	s_waitcnt vmcnt(15)
	v_pk_fma_f32 v[136:137], v[98:99], s[4:5], v[198:199] op_sel_hi:[1,0,1]
	v_pk_fma_f32 v[138:139], v[100:101], s[4:5], v[196:197] op_sel_hi:[1,0,1]
	global_load_dwordx4 v[196:199], v[186:187], off offset:-2048 nt
	s_waitcnt vmcnt(15)
	v_pk_fma_f32 v[140:141], v[102:103], s[4:5], v[202:203] op_sel_hi:[1,0,1]
	v_pk_fma_f32 v[142:143], v[104:105], s[4:5], v[200:201] op_sel_hi:[1,0,1]
	global_load_dwordx4 v[200:203], v[186:187], off offset:-1024 nt
	s_waitcnt vmcnt(15)
	v_pk_fma_f32 v[146:147], v[106:107], s[4:5], v[206:207] op_sel_hi:[1,0,1]
	v_pk_fma_f32 v[148:149], v[108:109], s[4:5], v[204:205] op_sel_hi:[1,0,1]
	global_load_dwordx4 v[204:207], v[186:187], off nt
	s_waitcnt vmcnt(15)
	v_pk_fma_f32 v[150:151], v[110:111], s[4:5], v[210:211] op_sel_hi:[1,0,1]
	v_pk_fma_f32 v[152:153], v[112:113], s[4:5], v[208:209] op_sel_hi:[1,0,1]
	global_load_dwordx4 v[208:211], v[186:187], off offset:1024 nt
	s_waitcnt vmcnt(15)
	v_pk_fma_f32 v[154:155], v[114:115], s[4:5], v[214:215] op_sel_hi:[1,0,1]
	v_pk_fma_f32 v[156:157], v[116:117], s[4:5], v[212:213] op_sel_hi:[1,0,1]
	global_load_dwordx4 v[212:215], v[186:187], off offset:2048 nt
	s_waitcnt vmcnt(15)
	v_pk_fma_f32 v[144:145], v[118:119], s[4:5], v[218:219] op_sel_hi:[1,0,1]
	v_pk_fma_f32 v[158:159], v[120:121], s[4:5], v[216:217] op_sel_hi:[1,0,1]
	global_load_dwordx4 v[216:219], v[186:187], off offset:3072 nt
	s_waitcnt vmcnt(15)
	v_pk_add_f32 v[130:131], v[130:131], v[220:221]
	v_pk_add_f32 v[128:129], v[128:129], v[222:223]
	global_load_dwordx4 v[220:223], v[68:69], off offset:-4096 nt
	s_waitcnt vmcnt(15)
	v_pk_add_f32 v[134:135], v[134:135], v[224:225]
	v_pk_add_f32 v[132:133], v[132:133], v[226:227]
	global_load_dwordx4 v[224:227], v[68:69], off offset:-3072 nt
	s_waitcnt vmcnt(15)
	v_pk_add_f32 v[138:139], v[138:139], v[228:229]
	v_pk_add_f32 v[136:137], v[136:137], v[230:231]
	global_load_dwordx4 v[228:231], v[68:69], off offset:-2048 nt
	s_waitcnt vmcnt(15)
	v_pk_add_f32 v[142:143], v[142:143], v[232:233]
	v_pk_add_f32 v[140:141], v[140:141], v[234:235]
	global_load_dwordx4 v[232:235], v[68:69], off offset:-1024 nt
	s_waitcnt vmcnt(15)
	v_pk_add_f32 v[146:147], v[146:147], v[238:239]
	v_pk_add_f32 v[148:149], v[148:149], v[236:237]
	global_load_dwordx4 v[236:239], v[68:69], off nt
	s_waitcnt vmcnt(15)
	v_pk_add_f32 v[150:151], v[150:151], v[242:243]
	v_pk_add_f32 v[152:153], v[152:153], v[240:241]
	global_load_dwordx4 v[240:243], v[68:69], off offset:1024 nt
	s_waitcnt vmcnt(15)
	v_pk_add_f32 v[154:155], v[154:155], v[246:247]
	v_pk_add_f32 v[156:157], v[156:157], v[244:245]
	global_load_dwordx4 v[244:247], v[68:69], off offset:2048 nt
	s_waitcnt vmcnt(15)
	v_pk_add_f32 v[144:145], v[144:145], v[250:251]
	v_pk_add_f32 v[158:159], v[158:159], v[248:249]
	global_load_dwordx4 v[248:251], v[68:69], off offset:3072 nt
	s_waitcnt vmcnt(15)
	v_pk_add_f32 v[128:129], v[128:129], v[190:191]
	v_pk_add_f32 v[130:131], v[130:131], v[188:189]
	s_waitcnt vmcnt(14)
	v_pk_add_f32 v[132:133], v[132:133], v[194:195]
	v_pk_add_f32 v[134:135], v[134:135], v[192:193]
	s_waitcnt vmcnt(13)
	v_pk_add_f32 v[136:137], v[136:137], v[198:199]
	v_pk_add_f32 v[174:175], v[138:139], v[196:197]
	s_waitcnt vmcnt(12)
	v_pk_add_f32 v[160:161], v[140:141], v[202:203]
	v_pk_add_f32 v[176:177], v[142:143], v[200:201]
	s_waitcnt vmcnt(11)
	v_pk_add_f32 v[178:179], v[146:147], v[206:207]
	v_pk_add_f32 v[148:149], v[148:149], v[204:205]
	s_waitcnt vmcnt(10)
	v_pk_add_f32 v[180:181], v[150:151], v[210:211]
	v_pk_add_f32 v[152:153], v[152:153], v[208:209]
	s_waitcnt vmcnt(9)
	v_pk_add_f32 v[154:155], v[154:155], v[214:215]
	v_pk_add_f32 v[156:157], v[156:157], v[212:213]
	s_waitcnt vmcnt(8)
	v_pk_add_f32 v[142:143], v[144:145], v[218:219]
	v_pk_add_f32 v[144:145], v[158:159], v[216:217]
	s_waitcnt vmcnt(7)
	v_pk_add_f32 v[164:165], v[128:129], v[222:223]
	v_pk_add_f32 v[162:163], v[130:131], v[220:221]
	s_waitcnt vmcnt(6)
	v_pk_add_f32 v[138:139], v[132:133], v[226:227]
	v_pk_add_f32 v[140:141], v[134:135], v[224:225]
	s_waitcnt vmcnt(5)
	v_pk_add_f32 v[122:123], v[136:137], v[230:231]
	v_pk_add_f32 v[146:147], v[174:175], v[228:229]
	s_waitcnt vmcnt(4)
	v_pk_add_f32 v[124:125], v[160:161], v[234:235]
	v_pk_add_f32 v[132:133], v[176:177], v[232:233]
	s_waitcnt vmcnt(3)
	v_pk_add_f32 v[134:135], v[148:149], v[236:237]
	v_pk_add_f32 v[126:127], v[178:179], v[238:239]
	v_mov_b32_e32 v160, v135
	s_waitcnt vmcnt(2)
	v_pk_add_f32 v[128:129], v[180:181], v[242:243]
	v_pk_add_f32 v[152:153], v[152:153], v[240:241]
	s_waitcnt vmcnt(1)
	v_pk_add_f32 v[130:131], v[154:155], v[246:247]
	v_pk_add_f32 v[136:137], v[156:157], v[244:245]
	v_mov_b32_e32 v154, v127
	v_mov_b32_e32 v157, v122
	v_mov_b32_e32 v156, v147
	v_mov_b32_e32 v122, v146
	v_mov_b32_e32 v146, v139
	v_mov_b32_e32 v147, v165
	v_mov_b32_e32 v139, v164
	s_waitcnt vmcnt(0)
	v_pk_add_f32 v[142:143], v[142:143], v[250:251]
	v_pk_add_f32 v[144:145], v[144:145], v[248:249]
	v_mov_b32_e32 v148, v143
	v_mov_b32_e32 v158, v145
	v_mov_b32_e32 v151, v128
	v_mov_b32_e32 v150, v153
	v_mov_b32_e32 v128, v152
	v_mov_b32_e32 v152, v141
	v_mov_b32_e32 v153, v163
	v_mov_b32_e32 v141, v162

	.amdhsa_kernel _Z14fwd_megakernel6Params
		.amdhsa_group_segment_fixed_size 0
		.amdhsa_private_segment_fixed_size 0
		.amdhsa_kernarg_size 392
		.amdhsa_user_sgpr_count 2
		.amdhsa_user_sgpr_dispatch_ptr 0
		.amdhsa_user_sgpr_queue_ptr 0
		.amdhsa_user_sgpr_kernarg_segment_ptr 1
		.amdhsa_user_sgpr_dispatch_id 0
		.amdhsa_user_sgpr_kernarg_preload_length 0
		.amdhsa_user_sgpr_kernarg_preload_offset 0
		.amdhsa_user_sgpr_private_segment_size 0
		.amdhsa_uses_dynamic_stack 0
		.amdhsa_enable_private_segment 0
		.amdhsa_system_sgpr_workgroup_id_x 1
		.amdhsa_system_sgpr_workgroup_id_y 0
		.amdhsa_system_sgpr_workgroup_id_z 0
		.amdhsa_system_sgpr_workgroup_info 0
		.amdhsa_system_vgpr_workitem_id 0
		.amdhsa_next_free_vgpr 256
		.amdhsa_next_free_sgpr 102
		.amdhsa_accum_offset 256
		.amdhsa_reserve_vcc 1
		.amdhsa_float_round_mode_32 0
		.amdhsa_float_round_mode_16_64 0
		.amdhsa_float_denorm_mode_32 3
		.amdhsa_float_denorm_mode_16_64 3
		.amdhsa_dx10_clamp 1
		.amdhsa_ieee_mode 1
		.amdhsa_fp16_overflow 0
		.amdhsa_tg_split 0
		.amdhsa_exception_fp_ieee_invalid_op 0
		.amdhsa_exception_fp_denorm_src 0
		.amdhsa_exception_fp_ieee_div_zero 0
		.amdhsa_exception_fp_ieee_overflow 0
		.amdhsa_exception_fp_ieee_underflow 0
		.amdhsa_exception_fp_ieee_inexact 0
		.amdhsa_exception_int_div_zero 0
	.end_amdhsa_kernel

amdhsa.kernels:
  - .agpr_count:     0
    .args:
      - .offset:         0
        .size:           136
        .value_kind:     by_value
      - .offset:         136
        .size:           4
        .value_kind:     hidden_block_count_x
      - .offset:         140
        .size:           4
        .value_kind:     hidden_block_count_y
      - .offset:         144
        .size:           4
        .value_kind:     hidden_block_count_z
      - .offset:         148
        .size:           2
        .value_kind:     hidden_group_size_x
      - .offset:         150
        .size:           2
        .value_kind:     hidden_group_size_y
      - .offset:         152
        .size:           2
        .value_kind:     hidden_group_size_z
      - .offset:         154
        .size:           2
        .value_kind:     hidden_remainder_x
      - .offset:         156
        .size:           2
        .value_kind:     hidden_remainder_y
      - .offset:         158
        .size:           2
        .value_kind:     hidden_remainder_z
      - .offset:         176
        .size:           8
        .value_kind:     hidden_global_offset_x
      - .offset:         184
        .size:           8
        .value_kind:     hidden_global_offset_y
      - .offset:         192
        .size:           8
        .value_kind:     hidden_global_offset_z
      - .offset:         200
        .size:           2
        .value_kind:     hidden_grid_dims
      - .offset:         256
        .size:           4
        .value_kind:     hidden_dynamic_lds_size
    .group_segment_fixed_size: 0
    .kernarg_segment_align: 8
    .kernarg_segment_size: 392
    .language:       OpenCL C
    .language_version:
      - 2
      - 0
    .max_flat_workgroup_size: 512
    .name:           _Z14fwd_megakernel6Params
    .private_segment_fixed_size: 0
    .sgpr_count:     108
    .sgpr_spill_count: 181
    .symbol:         _Z14fwd_megakernel6Params.kd
    .uniform_work_group_size: 1
    .uses_dynamic_stack: false
    .vgpr_count:     256
    .vgpr_spill_count: 0
    .wavefront_size: 64
